# attention item start: item id broadcast through LDS with ds_write/ds_read, no wait for the previous item's output stores
# speedup vs baseline: 1.0025x; 1.0025x over previous
.LBB0_830:
	s_cmp_lt_i32 s8, 6
	s_cselect_b64 s[0:1], -1, 0
	s_cmp_gt_i32 s9, 5
	s_cselect_b64 s[2:3], -1, 0
	s_and_b64 s[0:1], s[0:1], s[2:3]
	s_andn2_b64 vcc, exec, s[0:1]
	s_cbranch_vccnz .LBB0_873
	v_and_b32_e32 v1, 63, v144
	v_readlane_b32 s36, v254, 29
	v_lshlrev_b32_e32 v8, 2, v1
	v_readlane_b32 s48, v254, 41
	v_readlane_b32 s49, v254, 42
	v_readlane_b32 s50, v254, 43
	v_readlane_b32 s51, v254, 44
	s_nop 2
	global_load_dword v9, v8, s[48:49]
	s_nop 0
	global_load_dword v10, v8, s[50:51]
	v_readlane_b32 s4, v254, 0
	v_readlane_b32 s5, v254, 1
	v_readlane_b32 s6, v254, 2
	v_readlane_b32 s7, v254, 3
	s_nop 2
	global_load_dword v11, v8, s[4:5]
	s_nop 0
	global_load_dword v12, v8, s[6:7]
	v_readlane_b32 s40, v254, 33
	v_readlane_b32 s41, v254, 34
	v_mbcnt_lo_u32_b32 v0, -1, 0
	v_mbcnt_hi_u32_b32 v0, -1, v0
	v_and_b32_e32 v2, 64, v0
	v_add_u32_e32 v2, 64, v2
	v_xor_b32_e32 v4, 32, v0
	global_load_dword v21, v8, s[40:41]
	v_cmp_lt_i32_e32 vcc, v4, v2
	v_cmp_gt_u32_e64 s[6:7], 32, v1
	v_lshrrev_b32_e32 v19, 7, v144
	v_cndmask_b32_e32 v4, v0, v4, vcc
	v_lshlrev_b32_e32 v115, 2, v4
	v_xor_b32_e32 v4, 16, v0
	v_cmp_lt_i32_e32 vcc, v4, v2
	v_and_b32_e32 v5, 31, v144
	v_lshlrev_b32_e32 v145, 5, v19
	v_cndmask_b32_e32 v4, v0, v4, vcc
	v_lshlrev_b32_e32 v13, 2, v4
	v_xor_b32_e32 v4, 8, v0
	v_cmp_lt_i32_e32 vcc, v4, v2
	v_or_b32_e32 v150, v145, v5
	v_lshlrev_b32_e32 v152, 8, v5
	v_cndmask_b32_e32 v4, v0, v4, vcc
	v_lshlrev_b32_e32 v14, 2, v4
	v_xor_b32_e32 v4, 4, v0
	v_cmp_lt_i32_e32 vcc, v4, v2
	v_lshlrev_b32_e32 v153, 7, v5
	v_lshlrev_b32_e32 v5, 14, v19
	v_cndmask_b32_e32 v4, v0, v4, vcc
	v_lshlrev_b32_e32 v15, 2, v4
	v_xor_b32_e32 v4, 2, v0
	v_cmp_lt_i32_e32 vcc, v4, v2
	v_bfe_u32 v7, v144, 6, 1
	v_add3_u32 v154, 0, v5, v8
	v_cndmask_b32_e32 v4, v0, v4, vcc
	v_lshlrev_b32_e32 v16, 2, v4
	v_xor_b32_e32 v4, 1, v0
	v_lshrrev_b32_e32 v3, 6, v144
	v_cmp_lt_i32_e32 vcc, v4, v2
	v_bfe_u32 v18, v144, 5, 1
	v_and_b32_e32 v24, 15, v144
	v_lshlrev_b32_e32 v29, 3, v7
	v_cndmask_b32_e32 v0, v0, v4, vcc
	v_lshlrev_b32_e32 v4, 2, v3
	v_lshlrev_b32_e32 v6, 3, v3
	v_lshl_add_u32 v155, v3, 10, 0
	v_bitop3_b32 v3, v29, v24, v18 bitop3:0x36
	v_lshlrev_b32_e32 v156, 4, v3
	v_or_b32_e32 v30, v29, v18
	v_lshlrev_b32_e32 v17, 2, v0
	v_lshlrev_b32_e32 v0, 6, v7
	v_cmp_eq_u32_e64 s[4:5], 0, v7
	v_bitop3_b32 v7, v30, v24, 2 bitop3:0x36
	v_lshlrev_b32_e32 v157, 4, v7
	v_bitop3_b32 v7, v30, v24, 4 bitop3:0x36
	v_lshlrev_b32_e32 v158, 4, v7
	v_bitop3_b32 v7, v30, v24, 6 bitop3:0x36
	v_lshlrev_b32_e32 v159, 4, v7
	v_lshrrev_b32_e32 v27, 1, v144
	v_bfe_u32 v28, v144, 1, 3
	s_mov_b32 s0, 0x3fb8aa3b
	s_add_u32 s14, s90, 0x14948000
	s_addc_u32 s15, s91, 0
	v_readlane_b32 s8, v254, 4
	v_readlane_b32 s9, v254, 5
	v_mov_b32_e32 v113, 0
	v_lshlrev_b32_e32 v112, 4, v18
	s_mov_b32 s1, 0xc2ce8ed0
	s_add_u32 s16, s90, 0xf0f0000
	v_lshl_add_u64 v[118:119], s[8:9], 0, v[112:113]
	s_mov_b32 s8, 0x42b17218
	s_addc_u32 s17, s91, 0
	s_add_u32 s18, s90, 0x1bf98400
	s_waitcnt vmcnt(3)
	v_mul_f32_e32 v1, v9, v10
	ds_bpermute_b32 v1, v115, v1
	s_addc_u32 s19, s91, 0
	s_add_u32 s20, s90, 0x4040000
	s_addc_u32 s21, s91, 0
	s_waitcnt vmcnt(1)
	v_mul_f32_e32 v3, v11, v12
	s_waitcnt lgkmcnt(0)
	v_fmac_f32_e32 v1, v9, v10
	ds_bpermute_b32 v5, v13, v1
	ds_bpermute_b32 v3, v115, v3
	v_bfe_u32 v26, v144, 3, 3
	s_add_u32 s22, s90, 0x9898000
	v_lshrrev_b32_e32 v2, 5, v144
	s_waitcnt lgkmcnt(1)
	v_add_f32_e32 v1, v1, v5
	ds_bpermute_b32 v9, v14, v1
	s_waitcnt lgkmcnt(1)
	v_fmac_f32_e32 v3, v11, v12
	ds_bpermute_b32 v5, v13, v3
	v_or_b32_e32 v151, v6, v26
	s_addc_u32 s23, s91, 0
	s_waitcnt lgkmcnt(1)
	v_add_f32_e32 v1, v1, v9
	ds_bpermute_b32 v7, v15, v1
	s_waitcnt lgkmcnt(1)
	v_add_f32_e32 v3, v3, v5
	ds_bpermute_b32 v5, v14, v3
	v_bitop3_b32 v9, v18, v27, 7 bitop3:0x78
	v_lshlrev_b32_e32 v160, 4, v9
	s_waitcnt lgkmcnt(1)
	v_add_f32_e32 v1, v1, v7
	ds_bpermute_b32 v7, v16, v1
	s_waitcnt lgkmcnt(1)
	v_add_f32_e32 v3, v3, v5
	ds_bpermute_b32 v5, v15, v3
	v_bitop3_b32 v9, v18, v28, 2 bitop3:0x36
	v_lshlrev_b32_e32 v161, 4, v9
	s_waitcnt lgkmcnt(1)
	v_add_f32_e32 v1, v1, v7
	ds_bpermute_b32 v7, v17, v1
	s_waitcnt lgkmcnt(1)
	v_add_f32_e32 v3, v3, v5
	ds_bpermute_b32 v5, v16, v3
	v_bitop3_b32 v9, v18, v28, 4 bitop3:0x36
	v_lshlrev_b32_e32 v162, 4, v9
	s_waitcnt lgkmcnt(1)
	v_add_f32_e32 v1, v1, v7
	v_bitop3_b32 v9, v18, v28, 6 bitop3:0x36
	v_mul_f32_e32 v7, 0x3fb8aa3b, v1
	v_lshlrev_b32_e32 v163, 4, v9
	v_fma_f32 v9, v1, s0, -v7
	v_rndne_f32_e32 v10, v7
	v_fmac_f32_e32 v9, 0x32a5705f, v1
	v_sub_f32_e32 v7, v7, v10
	s_waitcnt lgkmcnt(0)
	v_add_f32_e32 v3, v3, v5
	v_add_f32_e32 v7, v7, v9
	v_cvt_i32_f32_e32 v9, v10
	s_waitcnt vmcnt(0)
	v_and_b32_e32 v10, 0x7fffffff, v21
	ds_bpermute_b32 v5, v17, v3
	ds_bpermute_b32 v10, v115, v10
	v_exp_f32_e32 v7, v7
	v_cmp_ngt_f32_e32 vcc, s1, v1
	v_bfe_u32 v20, v144, 4, 2
	s_waitcnt lgkmcnt(1)
	v_add_f32_e32 v3, v3, v5
	v_ldexp_f32 v5, v7, v9
	s_waitcnt lgkmcnt(0)
	v_max_f32_e32 v7, v10, v10
	v_max_f32_e64 v9, |v21|, |v21|
	v_max_f32_e32 v7, v9, v7
	ds_bpermute_b32 v9, v13, v7
	v_mul_f32_e32 v10, 0x3fb8aa3b, v3
	v_fma_f32 v11, v3, s0, -v10
	v_rndne_f32_e32 v12, v10
	v_fmac_f32_e32 v11, 0x32a5705f, v3
	s_waitcnt lgkmcnt(0)
	v_max_f32_e32 v9, v9, v9
	v_max_f32_e32 v7, v7, v9
	ds_bpermute_b32 v9, v14, v7
	v_sub_f32_e32 v10, v10, v12
	v_add_f32_e32 v10, v10, v11
	v_exp_f32_e32 v10, v10
	v_cvt_i32_f32_e32 v11, v12
	s_waitcnt lgkmcnt(0)
	v_max_f32_e32 v9, v9, v9
	v_max_f32_e32 v7, v7, v9
	ds_bpermute_b32 v9, v15, v7
	v_cndmask_b32_e32 v5, 0, v5, vcc
	v_mov_b32_e32 v12, 0x7f800000
	v_cmp_nlt_f32_e32 vcc, s8, v1
	v_and_b32_e32 v22, 8, v6
	s_waitcnt lgkmcnt(0)
	v_max_f32_e32 v9, v9, v9
	v_max_f32_e32 v7, v7, v9
	ds_bpermute_b32 v9, v16, v7
	v_cndmask_b32_e32 v1, v12, v5, vcc
	v_ldexp_f32 v5, v10, v11
	v_cmp_ngt_f32_e32 vcc, s1, v3
	v_and_b32_e32 v23, 4, v2
	s_waitcnt lgkmcnt(0)
	v_max_f32_e32 v9, v9, v9
	v_max_f32_e32 v7, v7, v9
	ds_bpermute_b32 v9, v17, v7
	v_cndmask_b32_e32 v5, 0, v5, vcc
	v_cmp_nlt_f32_e32 vcc, s8, v3
	v_lshrrev_b32_e32 v26, 1, v151
	s_add_u32 s24, s90, 0x18988000
	v_cndmask_b32_e32 v3, v12, v5, vcc
	v_sub_f32_e32 v1, v1, v3
	s_waitcnt lgkmcnt(0)
	v_max_f32_e32 v3, v9, v9
	v_max_f32_e32 v3, v7, v3
	v_add_f32_e32 v164, 0x3eb60549, v1
	v_mul_f32_e32 v1, 0x41000000, v3
	v_bitop3_b32 v25, v4, v24, v20 bitop3:0x36
	v_xor_b32_e32 v6, v26, v144
	v_mul_f32_e32 v165, 0x3f828f5c, v1
	v_or3_b32 v1, v20, v22, v23
	s_addc_u32 s25, s91, 0
	v_or3_b32 v2, v22, v23, v20
	v_lshlrev_b32_e32 v6, 3, v6
	v_lshl_add_u64 v[116:117], s[90:91], 0, v[112:113]
	v_lshlrev_b32_e32 v112, 11, v1
	v_lshlrev_b32_e32 v10, 4, v25
	v_mov_b32_e32 v11, v113
	s_mov_b64 s[12:13], src_shared_base
	v_readlane_b32 s37, v254, 30
	v_readlane_b32 s38, v254, 31
	v_readlane_b32 s39, v254, 32
	s_add_u32 s26, s90, 0x19a88000
	v_lshlrev_b32_e32 v2, 10, v2
	v_lshlrev_b32_e32 v4, 3, v25
	v_and_b32_e32 v6, 56, v6
	v_and_b32_e32 v19, 64, v144
	v_lshlrev_b32_e32 v8, 2, v18
	v_lshl_add_u64 v[10:11], v[112:113], 0, v[10:11]
	s_mov_b64 s[28:29], 0x20000
	v_bitop3_b32 v1, v26, 7, v144 bitop3:0x48
	v_mov_b32_e32 v3, 0x80
	s_addc_u32 s27, s91, 0
	v_lshlrev_b32_e32 v114, 3, v18
	v_cmp_ne_u32_e64 s[2:3], 0, v19
	s_mov_b32 s12, 0x41000000
	v_lshl_add_u64 v[120:121], v[10:11], 0, s[28:29]
	v_lshl_or_b32 v122, v1, 4, v3
	v_mov_b32_e32 v123, v113
	s_mov_b64 s[30:31], 0
	v_mov_b32_e32 v166, 1
	s_movk_i32 s52, 0x208
	s_movk_i32 s53, 0xfc0
	s_mov_b32 s54, 0x44000
	v_lshlrev_b32_e32 v124, 1, v0
	s_mov_b32 s55, 0x42480000
	s_mov_b64 s[34:35], 0x8000
	s_mov_b64 s[36:37], 0x10000
	s_mov_b64 s[38:39], 0x18000
	s_mov_b64 s[40:41], 0x80
	v_mov_b32_e32 v167, 0x358637bd
	s_mov_b32 s56, 0x800000
	v_lshlrev_b32_e32 v126, 1, v8
	s_mov_b32 s57, 0x8080
	v_mov_b32_e32 v168, 0x8000
	v_lshlrev_b32_e32 v128, 1, v2
	v_lshlrev_b32_e32 v130, 1, v4
	v_lshlrev_b32_e32 v132, 1, v6
	v_mov_b32_e32 v169, 0xff800000
	v_mov_b32_e32 v134, v199
	v_mov_b32_e32 v170, 0
	v_readlane_b32 s42, v254, 35
	v_readlane_b32 s43, v254, 36
	v_readlane_b32 s44, v254, 37
	v_readlane_b32 s45, v254, 38
	v_readlane_b32 s46, v254, 39
	v_readlane_b32 s47, v254, 40
	v_readlane_b32 s10, v254, 6
	v_readlane_b32 s11, v254, 7
	s_mov_b32 s66, 0
	s_mov_b64 s[62:63], exec
	v_readlane_b32 s64, v254, 11
	v_readlane_b32 s65, v254, 12
	s_and_b64 s[64:65], s[62:63], s[64:65]
	s_mov_b64 exec, s[64:65]
	s_cbranch_execz .Lpf_c
	v_mov_b32_e32 v219, v113
	v_mov_b32_e32 v218, v134
	v_lshl_add_u64 v[218:219], v[218:219], 2, s[18:19]
	global_atomic_add v216, v[218:219], v166, off sc0

.LBB0_833:
	s_mov_b64 s[0:1], exec
	v_readlane_b32 s8, v254, 11
	v_readlane_b32 s9, v254, 12
	s_and_b64 s[8:9], s[0:1], s[8:9]
	s_mov_b64 exec, s[8:9]
	s_cbranch_execz .LBB0_835
	v_mov_b32_e32 v135, v113
	v_lshl_add_u64 v[0:1], v[134:135], 2, s[18:19]
	s_mov_b64 s[8:9], src_shared_base
	s_add_i32 s8, 0, 0x10000
	s_cmp_lg_u32 s8, -1
	s_cselect_b32 s8, s8, 0
	s_cselect_b32 s9, s9, 0
	v_mov_b32_e32 v0, s8
	v_mov_b32_e32 v1, s9
	s_cmp_eq_u32 s66, 1
	s_cbranch_scc1 .Lds_skipw
	s_waitcnt vmcnt(0)
.Lds_skipw:
	s_mov_b32 s66, 0
	ds_write_b32 v0, v216
	s_waitcnt lgkmcnt(0)
.LBB0_835:
	s_or_b64 exec, exec, s[0:1]
	s_add_i32 s0, 0, 0x10000
	s_cmp_lg_u32 s0, -1
	s_cselect_b32 s0, s0, 0
	s_cselect_b32 s1, s13, 0
	v_mov_b32_e32 v0, s0
	v_mov_b32_e32 v1, s1
	s_waitcnt lgkmcnt(0)
	s_barrier
	ds_read_b32 v7, v0
	s_waitcnt lgkmcnt(0)
	s_barrier
	v_cmp_gt_i32_e32 vcc, s52, v7
	s_and_saveexec_b64 s[0:1], vcc
	s_xor_b64 s[42:43], exec, s[0:1]
	s_cbranch_execz .LBB0_861
	v_cmp_lt_i32_e32 vcc, 7, v7
	s_and_saveexec_b64 s[0:1], vcc
	s_xor_b64 s[0:1], exec, s[0:1]
	s_cbranch_execz .LBB0_838
	v_add_u32_e32 v0, -8, v7
	v_lshrrev_b32_e32 v4, 6, v0
	v_and_b32_e32 v0, 63, v0
	v_sub_u32_e32 v137, 64, v0
	v_lshlrev_b32_e32 v1, 12, v134
	v_lshlrev_b32_e32 v0, 6, v0
	v_lshlrev_b32_e32 v112, 23, v134
	v_bitop3_b32 v6, v0, s53, v1 bitop3:0x36
	v_lshl_add_u64 v[0:1], s[20:21], 0, v[112:113]
	v_lshlrev_b32_e32 v2, 8, v4
	v_mov_b32_e32 v3, v113
	v_lshl_add_u64 v[0:1], v[0:1], 0, v[2:3]
	v_lshl_add_u32 v2, v134, 3, v4
	v_lshlrev_b32_e32 v112, 7, v4
	v_lshlrev_b64 v[2:3], 20, v[2:3]
	v_lshlrev_b32_e32 v171, 6, v137
	v_lshl_add_u64 v[2:3], s[22:23], 0, v[2:3]
	v_mov_b32_e32 v135, v112
	v_mov_b64_e32 v[138:139], v[112:113]

.LBB0_857:
	s_or_b64 exec, exec, s[0:1]
	s_and_b64 s[8:9], s[4:5], s[8:9]
	s_waitcnt lgkmcnt(0)
	s_barrier
	s_and_saveexec_b64 s[0:1], s[8:9]
	s_cbranch_execz .LBB0_860
	ds_read2st64_b32 v[66:67], v154 offset1:1
	ds_read2st64_b32 v[68:69], v154 offset0:2 offset1:3
	ds_read2st64_b32 v[76:77], v154 offset0:4 offset1:5
	ds_read2st64_b32 v[78:79], v154 offset0:6 offset1:7
	v_cmp_lt_u32_e32 vcc, v150, v127
	s_waitcnt lgkmcnt(3)
	v_fma_f32 v72, v49, v64, -v67
	v_fma_f32 v71, v48, v64, -v66
	v_mul_f32_e32 v82, v72, v72
	v_fmac_f32_e32 v82, v71, v71
	s_waitcnt lgkmcnt(2)
	v_fma_f32 v73, v50, v64, -v68
	v_fmac_f32_e32 v82, v73, v73
	v_fma_f32 v74, v51, v64, -v69
	ds_read2st64_b32 v[48:49], v154 offset0:8 offset1:9
	v_fmac_f32_e32 v82, v74, v74
	s_waitcnt lgkmcnt(2)
	v_fma_f32 v75, v52, v64, -v76
	v_fmac_f32_e32 v82, v75, v75
	v_fma_f32 v76, v53, v64, -v77
	v_fmac_f32_e32 v82, v76, v76
	s_waitcnt lgkmcnt(1)
	v_fma_f32 v77, v54, v64, -v78
	v_fmac_f32_e32 v82, v77, v77
	v_fma_f32 v78, v55, v64, -v79
	ds_read2st64_b32 v[50:51], v154 offset0:10 offset1:11
	ds_read2st64_b32 v[52:53], v154 offset0:12 offset1:13
	ds_read2st64_b32 v[54:55], v154 offset0:14 offset1:15
	v_fmac_f32_e32 v82, v78, v78
	s_waitcnt lgkmcnt(3)
	v_fma_f32 v65, v56, v64, -v48
	v_fmac_f32_e32 v82, v65, v65
	v_fma_f32 v66, v57, v64, -v49
	v_fmac_f32_e32 v82, v66, v66
	s_waitcnt lgkmcnt(2)
	v_fma_f32 v67, v58, v64, -v50
	v_fmac_f32_e32 v82, v67, v67
	v_fma_f32 v69, v59, v64, -v51
	ds_read2st64_b32 v[48:49], v154 offset0:16 offset1:17
	v_fmac_f32_e32 v82, v69, v69
	s_waitcnt lgkmcnt(2)
	v_fma_f32 v70, v60, v64, -v52
	v_fmac_f32_e32 v82, v70, v70
	v_fma_f32 v68, v61, v64, -v53
	v_fmac_f32_e32 v82, v68, v68
	s_waitcnt lgkmcnt(1)
	v_fma_f32 v62, v62, v64, -v54
	v_fmac_f32_e32 v82, v62, v62
	v_fma_f32 v61, v63, v64, -v55
	ds_read2st64_b32 v[50:51], v154 offset0:18 offset1:19
	ds_read2st64_b32 v[58:59], v154 offset0:20 offset1:21
	ds_read2st64_b32 v[80:81], v154 offset0:22 offset1:23
	v_fmac_f32_e32 v82, v61, v61
	s_waitcnt lgkmcnt(3)
	v_fma_f32 v53, v32, v64, -v48
	v_fmac_f32_e32 v82, v53, v53
	v_fma_f32 v54, v33, v64, -v49
	v_fmac_f32_e32 v82, v54, v54
	s_waitcnt lgkmcnt(2)
	v_fma_f32 v55, v34, v64, -v50
	v_fmac_f32_e32 v82, v55, v55
	v_fma_f32 v56, v35, v64, -v51
	ds_read2st64_b32 v[32:33], v154 offset0:24 offset1:25
	v_fmac_f32_e32 v82, v56, v56
	s_waitcnt lgkmcnt(2)
	v_fma_f32 v57, v36, v64, -v58
	v_fmac_f32_e32 v82, v57, v57
	v_fma_f32 v58, v37, v64, -v59
	v_fmac_f32_e32 v82, v58, v58
	s_waitcnt lgkmcnt(1)
	v_fma_f32 v59, v38, v64, -v80
	v_fmac_f32_e32 v82, v59, v59
	v_fma_f32 v60, v39, v64, -v81
	ds_read2st64_b32 v[34:35], v154 offset0:26 offset1:27
	ds_read2st64_b32 v[36:37], v154 offset0:28 offset1:29
	ds_read2st64_b32 v[38:39], v154 offset0:30 offset1:31
	v_fmac_f32_e32 v82, v60, v60
	s_waitcnt lgkmcnt(3)
	v_fma_f32 v48, v40, v64, -v32
	v_fmac_f32_e32 v82, v48, v48
	v_fma_f32 v49, v41, v64, -v33
	v_fmac_f32_e32 v82, v49, v49
	s_waitcnt lgkmcnt(2)
	v_fma_f32 v50, v42, v64, -v34
	v_fmac_f32_e32 v82, v50, v50
	v_fma_f32 v51, v43, v64, -v35
	ds_read2st64_b32 v[32:33], v154 offset0:32 offset1:33
	v_fmac_f32_e32 v82, v51, v51
	s_waitcnt lgkmcnt(2)
	v_fma_f32 v52, v44, v64, -v36
	v_fmac_f32_e32 v82, v52, v52
	v_fma_f32 v45, v45, v64, -v37
	v_fmac_f32_e32 v82, v45, v45
	s_waitcnt lgkmcnt(1)
	v_fma_f32 v44, v46, v64, -v38
	v_fmac_f32_e32 v82, v44, v44
	v_fma_f32 v43, v47, v64, -v39
	ds_read2st64_b32 v[38:39], v154 offset0:34 offset1:35
	ds_read2st64_b32 v[40:41], v154 offset0:36 offset1:37
	ds_read2st64_b32 v[46:47], v154 offset0:38 offset1:39
	v_fmac_f32_e32 v82, v43, v43
	s_waitcnt lgkmcnt(3)
	v_fma_f32 v35, v16, v64, -v32
	v_fmac_f32_e32 v82, v35, v35
	v_fma_f32 v36, v17, v64, -v33
	v_fmac_f32_e32 v82, v36, v36
	s_waitcnt lgkmcnt(2)
	v_fma_f32 v37, v18, v64, -v38
	v_fmac_f32_e32 v82, v37, v37
	v_fma_f32 v38, v19, v64, -v39
	ds_read2st64_b32 v[16:17], v154 offset0:40 offset1:41
	v_fmac_f32_e32 v82, v38, v38
	s_waitcnt lgkmcnt(2)
	v_fma_f32 v39, v20, v64, -v40
	v_fmac_f32_e32 v82, v39, v39
	v_fma_f32 v40, v21, v64, -v41
	v_fmac_f32_e32 v82, v40, v40
	s_waitcnt lgkmcnt(1)
	v_fma_f32 v41, v22, v64, -v46
	v_fmac_f32_e32 v82, v41, v41
	v_fma_f32 v42, v23, v64, -v47
	ds_read2st64_b32 v[18:19], v154 offset0:42 offset1:43
	ds_read2st64_b32 v[20:21], v154 offset0:44 offset1:45
	ds_read2st64_b32 v[22:23], v154 offset0:46 offset1:47
	v_fmac_f32_e32 v82, v42, v42
	s_waitcnt lgkmcnt(3)
	v_fma_f32 v32, v24, v64, -v16
	v_fmac_f32_e32 v82, v32, v32
	v_fma_f32 v33, v25, v64, -v17
	v_fmac_f32_e32 v82, v33, v33
	s_waitcnt lgkmcnt(2)
	v_fma_f32 v26, v26, v64, -v18
	v_fmac_f32_e32 v82, v26, v26
	v_fma_f32 v34, v27, v64, -v19
	ds_read2st64_b32 v[16:17], v154 offset0:48 offset1:49
	v_fmac_f32_e32 v82, v34, v34
	s_waitcnt lgkmcnt(2)
	v_fma_f32 v28, v28, v64, -v20
	v_fmac_f32_e32 v82, v28, v28
	v_fma_f32 v27, v29, v64, -v21
	v_fmac_f32_e32 v82, v27, v27
	s_waitcnt lgkmcnt(1)
	v_fma_f32 v25, v30, v64, -v22
	v_fmac_f32_e32 v82, v25, v25
	v_fma_f32 v24, v31, v64, -v23
	ds_read2st64_b32 v[20:21], v154 offset0:50 offset1:51
	ds_read2st64_b32 v[22:23], v154 offset0:52 offset1:53
	ds_read2st64_b32 v[30:31], v154 offset0:54 offset1:55
	v_fmac_f32_e32 v82, v24, v24
	s_waitcnt lgkmcnt(3)
	v_fma_f32 v18, v0, v64, -v16
	v_fmac_f32_e32 v82, v18, v18
	v_fma_f32 v19, v1, v64, -v17
	v_fmac_f32_e32 v82, v19, v19
	s_waitcnt lgkmcnt(2)
	v_fma_f32 v20, v2, v64, -v20
	v_fmac_f32_e32 v82, v20, v20
	v_fma_f32 v21, v3, v64, -v21
	ds_read2st64_b32 v[2:3], v154 offset0:56 offset1:57
	v_fmac_f32_e32 v82, v21, v21
	s_waitcnt lgkmcnt(2)
	v_fma_f32 v22, v4, v64, -v22
	v_fmac_f32_e32 v82, v22, v22
	v_fma_f32 v23, v5, v64, -v23
	s_waitcnt lgkmcnt(1)
	v_pk_fma_f32 v[16:17], v[6:7], v[64:65], v[30:31] op_sel_hi:[1,0,1] neg_lo:[0,0,1] neg_hi:[0,0,1]
	v_fmac_f32_e32 v82, v23, v23
	v_pk_mul_f32 v[0:1], v[16:17], v[16:17]
	ds_read2st64_b32 v[4:5], v154 offset0:58 offset1:59
	ds_read2st64_b32 v[6:7], v154 offset0:60 offset1:61
	ds_read2st64_b32 v[30:31], v154 offset0:62 offset1:63
	v_add_f32_e32 v0, v82, v0
	v_add_f32_e32 v29, v0, v1
	s_waitcnt lgkmcnt(3)
	v_pk_fma_f32 v[0:1], v[8:9], v[64:65], v[2:3] op_sel_hi:[1,0,1] neg_lo:[0,0,1] neg_hi:[0,0,1]
	s_waitcnt lgkmcnt(2)
	v_pk_fma_f32 v[4:5], v[10:11], v[64:65], v[4:5] op_sel_hi:[1,0,1] neg_lo:[0,0,1] neg_hi:[0,0,1]
	v_pk_mul_f32 v[2:3], v[0:1], v[0:1]
	s_nop 0
	v_add_f32_e32 v2, v29, v2
	v_add_f32_e32 v8, v2, v3
	v_pk_mul_f32 v[2:3], v[4:5], v[4:5]
	s_nop 0
	v_add_f32_e32 v2, v8, v2
	v_add_f32_e32 v8, v2, v3
	s_waitcnt lgkmcnt(1)
	v_pk_fma_f32 v[2:3], v[12:13], v[64:65], v[6:7] op_sel_hi:[1,0,1] neg_lo:[0,0,1] neg_hi:[0,0,1]
	s_nop 0
	v_pk_mul_f32 v[6:7], v[2:3], v[2:3]
	s_nop 0
	v_add_f32_e32 v6, v8, v6
	v_add_f32_e32 v10, v6, v7
	s_waitcnt lgkmcnt(0)
	v_pk_fma_f32 v[6:7], v[14:15], v[64:65], v[30:31] op_sel_hi:[1,0,1] neg_lo:[0,0,1] neg_hi:[0,0,1]
	s_nop 0
	v_pk_mul_f32 v[8:9], v[6:7], v[6:7]
	s_nop 0
	v_add_f32_e32 v8, v10, v8
	v_add_f32_e32 v10, v8, v9
	ds_bpermute_b32 v11, v115, v10
	s_and_b64 exec, exec, vcc
	s_cbranch_execz .LBB0_860
	s_mov_b32 s66, 1
	v_mov_b32_e32 v137, v113
	v_lshlrev_b64 v[8:9], 11, v[136:137]
	v_lshl_add_u64 v[8:9], s[14:15], 0, v[8:9]
	v_mov_b32_e32 v127, v113
	v_lshl_add_u64 v[8:9], v[138:139], 1, v[8:9]
	global_load_dwordx4 v[12:15], v[118:119], off
	global_load_dwordx4 v[80:83], v[118:119], off offset:32
	v_lshl_add_u64 v[8:9], v[8:9], 0, v[126:127]
	global_load_dwordx2 v[30:31], v[8:9], off
	global_load_dwordx2 v[46:47], v[8:9], off offset:16
	s_waitcnt lgkmcnt(0)
	v_add_f32_e32 v10, v10, v11
	v_fmamk_f32 v10, v10, 0x3c000000, v167
	v_mul_f32_e32 v11, 0x4b800000, v10
	v_cmp_gt_f32_e32 vcc, s56, v10
	s_nop 1
	v_cndmask_b32_e32 v10, v10, v11, vcc
	v_rsq_f32_e32 v10, v10
	v_ashrrev_i32_e32 v11, 5, v135
	v_mul_f32_e32 v29, 0x45800000, v10
	v_cndmask_b32_e32 v10, v10, v29, vcc
	v_mul_f32_e32 v10, 0x3f24fd5c, v10
	v_mul_f32_e32 v29, v71, v10
	v_mul_f32_e32 v63, v72, v10
	v_mul_f32_e32 v64, v73, v10
	v_mul_f32_e32 v71, v74, v10
	v_mul_f32_e32 v72, v75, v10
	v_mul_f32_e32 v73, v76, v10
	v_mul_f32_e32 v74, v77, v10
	v_mul_f32_e32 v75, v78, v10
	v_mul_f32_e32 v62, v62, v10
	v_mul_f32_e32 v61, v61, v10
	v_mul_f32_e32 v53, v53, v10
	v_mul_f32_e32 v54, v54, v10
	v_mul_f32_e32 v55, v55, v10
	v_mul_f32_e32 v56, v56, v10
	v_mul_f32_e32 v57, v57, v10
	v_mul_f32_e32 v58, v58, v10
	v_mul_f32_e32 v59, v59, v10
	v_mul_f32_e32 v60, v60, v10
	v_mul_f32_e32 v43, v43, v10
	v_mul_f32_e32 v45, v45, v10
	v_mul_f32_e32 v44, v44, v10
	v_mul_f32_e32 v35, v35, v10
	v_mul_f32_e32 v36, v36, v10
	v_mul_f32_e32 v37, v37, v10
	v_mul_f32_e32 v38, v38, v10
	v_mul_f32_e32 v39, v39, v10
	v_mul_f32_e32 v40, v40, v10
	v_mul_f32_e32 v41, v41, v10
	v_mul_f32_e32 v42, v42, v10
	v_mul_f32_e32 v26, v26, v10
	v_mul_f32_e32 v28, v28, v10
	v_mul_f32_e32 v27, v27, v10
	v_mul_f32_e32 v25, v25, v10
	v_mul_f32_e32 v24, v24, v10
	v_mul_f32_e32 v18, v18, v10
	v_mul_f32_e32 v19, v19, v10
	v_mul_f32_e32 v20, v20, v10
	v_mul_f32_e32 v21, v21, v10
	v_mul_f32_e32 v22, v22, v10
	v_mul_f32_e32 v23, v23, v10
	v_mul_f32_e32 v16, v16, v10
	v_mul_f32_e32 v17, v17, v10
	v_mul_f32_e32 v0, v0, v10
	v_mul_f32_e32 v1, v1, v10
	v_mul_f32_e32 v4, v4, v10
	v_mul_f32_e32 v5, v5, v10
	v_mul_f32_e32 v2, v2, v10
	v_mul_f32_e32 v3, v3, v10
	v_mul_f32_e32 v6, v6, v10
	v_mul_f32_e32 v7, v7, v10
	s_waitcnt vmcnt(3)
	v_mul_f32_e32 v12, v29, v12
	v_mul_f32_e32 v13, v63, v13
	v_mul_f32_e32 v14, v64, v14
	v_mul_f32_e32 v15, v71, v15
	s_waitcnt vmcnt(2)
	v_mul_f32_e32 v29, v72, v80
	v_mul_f32_e32 v63, v73, v81
	s_waitcnt vmcnt(1)
	v_lshlrev_b32_e32 v72, 16, v30
	v_and_b32_e32 v30, 0xffff0000, v30
	v_lshlrev_b32_e32 v73, 16, v31
	v_and_b32_e32 v31, 0xffff0000, v31
	v_mul_f32_e32 v64, v74, v82
	v_mul_f32_e32 v71, v75, v83
	s_waitcnt vmcnt(0)
	v_lshlrev_b32_e32 v74, 16, v46
	v_and_b32_e32 v46, 0xffff0000, v46
	v_lshlrev_b32_e32 v75, 16, v47
	v_and_b32_e32 v47, 0xffff0000, v47
	v_mul_f32_e32 v12, v12, v72
	v_mul_f32_e32 v13, v13, v30
	v_mul_f32_e32 v14, v14, v73
	v_mul_f32_e32 v15, v15, v31
	v_mul_f32_e32 v29, v29, v74
	v_mul_f32_e32 v30, v63, v46
	v_mul_f32_e32 v31, v64, v75
	v_mul_f32_e32 v46, v71, v47
	v_cvt_pk_bf16_f32 v47, v12, v13
	v_cvt_pk_bf16_f32 v63, v14, v15
	v_cvt_pk_bf16_f32 v14, v29, v30
	v_cvt_pk_bf16_f32 v15, v31, v46
	v_mul_f32_e32 v64, v67, v10
	v_cndmask_b32_e64 v12, v63, v15, s[6:7]
	v_cndmask_b32_e64 v13, v47, v14, s[6:7]
	ds_bpermute_b32 v29, v115, v13
	ds_bpermute_b32 v46, v115, v12
	v_mad_i64_i32 v[12:13], s[8:9], v11, s57, v[136:137]
	v_lshlrev_b64 v[12:13], 6, v[12:13]
	v_lshl_add_u64 v[30:31], v[116:117], 0, v[12:13]
	s_waitcnt lgkmcnt(0)
	v_cndmask_b32_e64 v15, v15, v46, s[6:7]
	v_cndmask_b32_e64 v14, v14, v29, s[6:7]
	v_cndmask_b32_e64 v13, v46, v63, s[6:7]
	v_cndmask_b32_e64 v12, v29, v47, s[6:7]
	global_store_dwordx4 v[30:31], v[12:15], off
	global_load_dwordx4 v[12:15], v[118:119], off offset:64
	s_nop 0
	global_load_dwordx2 v[46:47], v[8:9], off offset:32
	global_load_dwordx4 v[72:75], v[118:119], off offset:96
	global_load_dwordx2 v[76:77], v[8:9], off offset:48
	v_mul_f32_e32 v29, v65, v10
	v_mul_f32_e32 v63, v66, v10
	v_mul_f32_e32 v65, v69, v10
	v_mul_f32_e32 v66, v70, v10
	v_mul_f32_e32 v67, v68, v10
	s_waitcnt vmcnt(3)
	v_mul_f32_e32 v12, v29, v12
	s_waitcnt vmcnt(2)
	v_lshlrev_b32_e32 v29, 16, v46
	v_mul_f32_e32 v13, v63, v13
	v_and_b32_e32 v46, 0xffff0000, v46
	v_mul_f32_e32 v14, v64, v14
	v_lshlrev_b32_e32 v63, 16, v47
	v_mul_f32_e32 v15, v65, v15
	v_and_b32_e32 v47, 0xffff0000, v47
	s_waitcnt vmcnt(1)
	v_mul_f32_e32 v64, v66, v72
	s_waitcnt vmcnt(0)
	v_lshlrev_b32_e32 v65, 16, v76
	v_mul_f32_e32 v66, v67, v73
	v_and_b32_e32 v67, 0xffff0000, v76
	v_mul_f32_e32 v62, v62, v74
	v_lshlrev_b32_e32 v68, 16, v77
	v_mul_f32_e32 v61, v61, v75
	v_and_b32_e32 v69, 0xffff0000, v77
	v_mul_f32_e32 v12, v12, v29
	v_mul_f32_e32 v13, v13, v46
	v_mul_f32_e32 v14, v14, v63
	v_mul_f32_e32 v15, v15, v47
	v_mul_f32_e32 v29, v64, v65
	v_mul_f32_e32 v46, v66, v67
	v_mul_f32_e32 v47, v62, v68
	v_mul_f32_e32 v61, v61, v69
	v_cvt_pk_bf16_f32 v12, v12, v13
	v_cvt_pk_bf16_f32 v13, v14, v15
	v_cvt_pk_bf16_f32 v14, v29, v46
	v_cvt_pk_bf16_f32 v15, v47, v61
	s_nop 0
	v_cndmask_b32_e64 v29, v13, v15, s[6:7]
	v_cndmask_b32_e64 v46, v12, v14, s[6:7]
	ds_bpermute_b32 v29, v115, v29
	ds_bpermute_b32 v46, v115, v46
	s_waitcnt lgkmcnt(1)
	v_cndmask_b32_e64 v15, v15, v29, s[6:7]
	s_waitcnt lgkmcnt(0)
	v_cndmask_b32_e64 v14, v14, v46, s[6:7]
	v_cndmask_b32_e64 v13, v29, v13, s[6:7]
	v_cndmask_b32_e64 v12, v46, v12, s[6:7]
	global_store_dwordx4 v[30:31], v[12:15], off offset:32
	global_load_dwordx4 v[12:15], v[118:119], off offset:128
	s_nop 0
	global_load_dwordx2 v[30:31], v[8:9], off offset:64
	global_load_dwordx4 v[62:65], v[118:119], off offset:160
	global_load_dwordx2 v[46:47], v[8:9], off offset:80
	v_or_b32_e32 v29, 1, v11
	s_waitcnt vmcnt(3)
	v_mul_f32_e32 v12, v53, v12
	s_waitcnt vmcnt(2)
	v_lshlrev_b32_e32 v53, 16, v30
	v_mul_f32_e32 v13, v54, v13
	v_and_b32_e32 v30, 0xffff0000, v30
	v_mul_f32_e32 v14, v55, v14
	v_lshlrev_b32_e32 v54, 16, v31
	v_mul_f32_e32 v15, v56, v15
	v_and_b32_e32 v31, 0xffff0000, v31
	s_waitcnt vmcnt(1)
	v_mul_f32_e32 v55, v57, v62
	s_waitcnt vmcnt(0)
	v_lshlrev_b32_e32 v56, 16, v46
	v_mul_f32_e32 v57, v58, v63
	v_and_b32_e32 v46, 0xffff0000, v46
	v_mul_f32_e32 v58, v59, v64
	v_lshlrev_b32_e32 v59, 16, v47
	v_mul_f32_e32 v60, v60, v65
	v_and_b32_e32 v47, 0xffff0000, v47
	v_mul_f32_e32 v12, v12, v53
	v_mul_f32_e32 v13, v13, v30
	v_mul_f32_e32 v14, v14, v54
	v_mul_f32_e32 v15, v15, v31
	v_mul_f32_e32 v30, v55, v56
	v_mul_f32_e32 v31, v57, v46
	v_mul_f32_e32 v46, v58, v59
	v_mul_f32_e32 v47, v60, v47
	v_cvt_pk_bf16_f32 v53, v12, v13
	v_cvt_pk_bf16_f32 v54, v14, v15
	v_cvt_pk_bf16_f32 v14, v30, v31
	v_cvt_pk_bf16_f32 v15, v46, v47
	s_nop 0
	v_cndmask_b32_e64 v12, v54, v15, s[6:7]
	v_cndmask_b32_e64 v13, v53, v14, s[6:7]
	ds_bpermute_b32 v46, v115, v13
	ds_bpermute_b32 v47, v115, v12
	v_mad_i64_i32 v[12:13], s[8:9], v29, s57, v[136:137]
	v_lshlrev_b64 v[12:13], 6, v[12:13]
	v_lshl_add_u64 v[30:31], v[116:117], 0, v[12:13]
	s_waitcnt lgkmcnt(0)
	v_cndmask_b32_e64 v15, v15, v47, s[6:7]
	v_cndmask_b32_e64 v14, v14, v46, s[6:7]
	v_cndmask_b32_e64 v13, v47, v54, s[6:7]
	v_cndmask_b32_e64 v12, v46, v53, s[6:7]
	global_store_dwordx4 v[30:31], v[12:15], off
	global_load_dwordx4 v[12:15], v[118:119], off offset:192
	s_nop 0
	global_load_dwordx2 v[46:47], v[8:9], off offset:96
	global_load_dwordx4 v[54:57], v[118:119], off offset:224
	global_load_dwordx2 v[58:59], v[8:9], off offset:112
	v_mul_f32_e32 v29, v48, v10
	v_mul_f32_e32 v48, v49, v10
	v_mul_f32_e32 v49, v50, v10
	v_mul_f32_e32 v50, v51, v10
	v_mul_f32_e32 v51, v52, v10
	s_waitcnt vmcnt(3)
	v_mul_f32_e32 v12, v29, v12
	s_waitcnt vmcnt(2)
	v_lshlrev_b32_e32 v29, 16, v46
	v_mul_f32_e32 v13, v48, v13
	v_and_b32_e32 v46, 0xffff0000, v46
	v_mul_f32_e32 v14, v49, v14
	v_lshlrev_b32_e32 v48, 16, v47
	v_mul_f32_e32 v15, v50, v15
	v_and_b32_e32 v47, 0xffff0000, v47
	s_waitcnt vmcnt(1)
	v_mul_f32_e32 v49, v51, v54
	s_waitcnt vmcnt(0)
	v_lshlrev_b32_e32 v50, 16, v58
	v_mul_f32_e32 v43, v43, v57
	v_and_b32_e32 v53, 0xffff0000, v59
	v_mul_f32_e32 v45, v45, v55
	v_and_b32_e32 v51, 0xffff0000, v58
	v_mul_f32_e32 v44, v44, v56
	v_lshlrev_b32_e32 v52, 16, v59
	v_mul_f32_e32 v12, v12, v29
	v_mul_f32_e32 v13, v13, v46
	v_mul_f32_e32 v14, v14, v48
	v_mul_f32_e32 v15, v15, v47
	v_mul_f32_e32 v29, v49, v50
	v_mul_f32_e32 v43, v43, v53
	v_mul_f32_e32 v45, v45, v51
	v_mul_f32_e32 v44, v44, v52
	v_cvt_pk_bf16_f32 v12, v12, v13
	v_cvt_pk_bf16_f32 v13, v14, v15
	v_cvt_pk_bf16_f32 v14, v29, v45
	v_cvt_pk_bf16_f32 v15, v44, v43
	s_nop 0
	v_cndmask_b32_e64 v29, v13, v15, s[6:7]
	v_cndmask_b32_e64 v43, v12, v14, s[6:7]
	ds_bpermute_b32 v29, v115, v29
	ds_bpermute_b32 v43, v115, v43
	s_waitcnt lgkmcnt(1)
	v_cndmask_b32_e64 v15, v15, v29, s[6:7]
	s_waitcnt lgkmcnt(0)
	v_cndmask_b32_e64 v14, v14, v43, s[6:7]
	v_cndmask_b32_e64 v13, v29, v13, s[6:7]
	v_cndmask_b32_e64 v12, v43, v12, s[6:7]
	global_store_dwordx4 v[30:31], v[12:15], off offset:32
	global_load_dwordx4 v[12:15], v[118:119], off offset:256
	s_nop 0
	global_load_dwordx2 v[30:31], v[8:9], off offset:128
	global_load_dwordx4 v[44:47], v[118:119], off offset:288
	global_load_dwordx2 v[48:49], v[8:9], off offset:144
	v_or_b32_e32 v29, 2, v11
	v_or_b32_e32 v11, 3, v11
	s_waitcnt vmcnt(3)
	v_mul_f32_e32 v12, v35, v12
	s_waitcnt vmcnt(2)
	v_lshlrev_b32_e32 v35, 16, v30
	v_mul_f32_e32 v13, v36, v13
	v_and_b32_e32 v30, 0xffff0000, v30
	v_mul_f32_e32 v14, v37, v14
	v_lshlrev_b32_e32 v36, 16, v31
	v_mul_f32_e32 v15, v38, v15
	v_and_b32_e32 v31, 0xffff0000, v31
	s_waitcnt vmcnt(1)
	v_mul_f32_e32 v37, v39, v44
	s_waitcnt vmcnt(0)
	v_lshlrev_b32_e32 v38, 16, v48
	v_mul_f32_e32 v39, v40, v45
	v_and_b32_e32 v40, 0xffff0000, v48
	v_mul_f32_e32 v41, v41, v46
	v_lshlrev_b32_e32 v43, 16, v49
	v_mul_f32_e32 v42, v42, v47
	v_and_b32_e32 v44, 0xffff0000, v49
	v_mul_f32_e32 v12, v12, v35
	v_mul_f32_e32 v13, v13, v30
	v_mul_f32_e32 v14, v14, v36
	v_mul_f32_e32 v15, v15, v31
	v_mul_f32_e32 v30, v37, v38
	v_mul_f32_e32 v31, v39, v40
	v_mul_f32_e32 v35, v41, v43
	v_mul_f32_e32 v36, v42, v44
	v_cvt_pk_bf16_f32 v37, v12, v13
	v_cvt_pk_bf16_f32 v38, v14, v15
	v_cvt_pk_bf16_f32 v14, v30, v31
	v_cvt_pk_bf16_f32 v15, v35, v36
	s_nop 0
	v_cndmask_b32_e64 v12, v38, v15, s[6:7]
	v_cndmask_b32_e64 v13, v37, v14, s[6:7]
	ds_bpermute_b32 v35, v115, v13
	ds_bpermute_b32 v36, v115, v12
	v_mad_i64_i32 v[12:13], s[8:9], v29, s57, v[136:137]
	v_lshlrev_b64 v[12:13], 6, v[12:13]
	v_lshl_add_u64 v[30:31], v[116:117], 0, v[12:13]
	s_waitcnt lgkmcnt(0)
	v_cndmask_b32_e64 v15, v15, v36, s[6:7]
	v_cndmask_b32_e64 v14, v14, v35, s[6:7]
	v_cndmask_b32_e64 v13, v36, v38, s[6:7]
	v_cndmask_b32_e64 v12, v35, v37, s[6:7]
	global_store_dwordx4 v[30:31], v[12:15], off
	global_load_dwordx4 v[12:15], v[118:119], off offset:320
	s_nop 0
	global_load_dwordx2 v[40:41], v[8:9], off offset:160
	global_load_dwordx4 v[36:39], v[118:119], off offset:352
	global_load_dwordx2 v[42:43], v[8:9], off offset:176
	v_mul_f32_e32 v29, v32, v10
	v_mul_f32_e32 v32, v33, v10
	v_mul_f32_e32 v33, v34, v10
	s_waitcnt vmcnt(3)
	v_mul_f32_e32 v12, v29, v12
	s_waitcnt vmcnt(2)
	v_lshlrev_b32_e32 v29, 16, v40
	v_mul_f32_e32 v13, v32, v13
	v_and_b32_e32 v32, 0xffff0000, v40
	v_mul_f32_e32 v14, v26, v14
	v_lshlrev_b32_e32 v26, 16, v41
	v_mul_f32_e32 v15, v33, v15
	v_and_b32_e32 v33, 0xffff0000, v41
	s_waitcnt vmcnt(1)
	v_mul_f32_e32 v28, v28, v36
	v_mul_f32_e32 v27, v27, v37
	v_mul_f32_e32 v25, v25, v38
	s_waitcnt vmcnt(0)
	v_lshlrev_b32_e32 v36, 16, v43
	v_mul_f32_e32 v24, v24, v39
	v_and_b32_e32 v37, 0xffff0000, v43
	v_lshlrev_b32_e32 v34, 16, v42
	v_and_b32_e32 v35, 0xffff0000, v42
	v_mul_f32_e32 v12, v12, v29
	v_mul_f32_e32 v13, v13, v32
	v_mul_f32_e32 v14, v14, v26
	v_mul_f32_e32 v15, v15, v33
	v_mul_f32_e32 v25, v25, v36
	v_mul_f32_e32 v24, v24, v37
	v_mul_f32_e32 v26, v28, v34
	v_mul_f32_e32 v27, v27, v35
	v_cvt_pk_bf16_f32 v12, v12, v13
	v_cvt_pk_bf16_f32 v13, v14, v15
	v_cvt_pk_bf16_f32 v14, v26, v27
	v_cvt_pk_bf16_f32 v15, v25, v24
	s_nop 0
	v_cndmask_b32_e64 v24, v13, v15, s[6:7]
	v_cndmask_b32_e64 v25, v12, v14, s[6:7]
	ds_bpermute_b32 v24, v115, v24
	ds_bpermute_b32 v25, v115, v25
	s_waitcnt lgkmcnt(1)
	v_cndmask_b32_e64 v15, v15, v24, s[6:7]
	s_waitcnt lgkmcnt(0)
	v_cndmask_b32_e64 v14, v14, v25, s[6:7]
	v_cndmask_b32_e64 v13, v24, v13, s[6:7]
	v_cndmask_b32_e64 v12, v25, v12, s[6:7]
	global_store_dwordx4 v[30:31], v[12:15], off offset:32
	global_load_dwordx4 v[12:15], v[118:119], off offset:384
	s_nop 0
	global_load_dwordx2 v[28:29], v[8:9], off offset:192
	global_load_dwordx4 v[24:27], v[118:119], off offset:416
	global_load_dwordx2 v[30:31], v[8:9], off offset:208
	s_waitcnt vmcnt(3)
	v_mul_f32_e32 v12, v18, v12
	s_waitcnt vmcnt(2)
	v_lshlrev_b32_e32 v18, 16, v28
	v_mul_f32_e32 v13, v19, v13
	v_and_b32_e32 v19, 0xffff0000, v28
	v_mul_f32_e32 v14, v20, v14
	v_lshlrev_b32_e32 v20, 16, v29
	v_mul_f32_e32 v15, v21, v15
	v_and_b32_e32 v21, 0xffff0000, v29
	s_waitcnt vmcnt(1)
	v_mul_f32_e32 v22, v22, v24
	s_waitcnt vmcnt(0)
	v_lshlrev_b32_e32 v24, 16, v30
	v_mul_f32_e32 v23, v23, v25
	v_and_b32_e32 v25, 0xffff0000, v30
	v_mul_f32_e32 v16, v16, v26
	v_lshlrev_b32_e32 v26, 16, v31
	v_mul_f32_e32 v17, v17, v27
	v_and_b32_e32 v27, 0xffff0000, v31
	v_mul_f32_e32 v12, v12, v18
	v_mul_f32_e32 v13, v13, v19
	v_mul_f32_e32 v14, v14, v20
	v_mul_f32_e32 v15, v15, v21
	v_mul_f32_e32 v18, v22, v24
	v_mul_f32_e32 v19, v23, v25
	v_mul_f32_e32 v16, v16, v26
	v_mul_f32_e32 v17, v17, v27
	v_cvt_pk_bf16_f32 v22, v12, v13
	v_cvt_pk_bf16_f32 v23, v14, v15
	v_cvt_pk_bf16_f32 v14, v18, v19
	v_cvt_pk_bf16_f32 v15, v16, v17
	s_nop 0
	v_cndmask_b32_e64 v12, v23, v15, s[6:7]
	v_cndmask_b32_e64 v13, v22, v14, s[6:7]
	ds_bpermute_b32 v16, v115, v13
	ds_bpermute_b32 v17, v115, v12
	v_mad_i64_i32 v[12:13], s[8:9], v11, s57, v[136:137]
	v_lshlrev_b64 v[12:13], 6, v[12:13]
	v_lshl_add_u64 v[20:21], v[116:117], 0, v[12:13]
	s_waitcnt lgkmcnt(0)
	v_cndmask_b32_e64 v15, v15, v17, s[6:7]
	v_cndmask_b32_e64 v14, v14, v16, s[6:7]
	v_cndmask_b32_e64 v13, v17, v23, s[6:7]
	v_cndmask_b32_e64 v12, v16, v22, s[6:7]
	global_store_dwordx4 v[20:21], v[12:15], off
	global_load_dwordx4 v[12:15], v[118:119], off offset:448
	s_nop 0
	global_load_dwordx2 v[22:23], v[8:9], off offset:224
	global_load_dwordx4 v[16:19], v[118:119], off offset:480
	s_nop 0
	global_load_dwordx2 v[8:9], v[8:9], off offset:240
	s_waitcnt vmcnt(3)
	v_mul_f32_e32 v0, v0, v12
	s_waitcnt vmcnt(2)
	v_lshlrev_b32_e32 v10, 16, v22
	v_mul_f32_e32 v1, v1, v13
	v_and_b32_e32 v11, 0xffff0000, v22
	v_mul_f32_e32 v4, v4, v14
	v_lshlrev_b32_e32 v12, 16, v23
	v_mul_f32_e32 v5, v5, v15
	v_and_b32_e32 v13, 0xffff0000, v23
	s_waitcnt vmcnt(1)
	v_mul_f32_e32 v2, v2, v16
	s_waitcnt vmcnt(0)
	v_lshlrev_b32_e32 v14, 16, v8
	v_mul_f32_e32 v3, v3, v17
	v_and_b32_e32 v8, 0xffff0000, v8
	v_mul_f32_e32 v6, v6, v18
	v_lshlrev_b32_e32 v15, 16, v9
	v_mul_f32_e32 v7, v7, v19
	v_and_b32_e32 v9, 0xffff0000, v9
	v_mul_f32_e32 v0, v0, v10
	v_mul_f32_e32 v1, v1, v11
	v_mul_f32_e32 v4, v4, v12
	v_mul_f32_e32 v5, v5, v13
	v_mul_f32_e32 v2, v2, v14
	v_mul_f32_e32 v3, v3, v8
	v_mul_f32_e32 v6, v6, v15
	v_mul_f32_e32 v7, v7, v9
	v_cvt_pk_bf16_f32 v0, v0, v1
	v_cvt_pk_bf16_f32 v1, v4, v5
	v_cvt_pk_bf16_f32 v2, v2, v3
	v_cvt_pk_bf16_f32 v3, v6, v7
	s_nop 0
	v_cndmask_b32_e64 v4, v1, v3, s[6:7]
	v_cndmask_b32_e64 v5, v0, v2, s[6:7]
	ds_bpermute_b32 v4, v115, v4
	ds_bpermute_b32 v5, v115, v5
	s_waitcnt lgkmcnt(1)
	v_cndmask_b32_e64 v3, v3, v4, s[6:7]
	s_waitcnt lgkmcnt(0)
	v_cndmask_b32_e64 v2, v2, v5, s[6:7]
	v_cndmask_b32_e64 v1, v4, v1, s[6:7]
	v_cndmask_b32_e64 v0, v5, v0, s[6:7]
	global_store_dwordx4 v[20:21], v[0:3], off offset:32
